# v46 plus one exp interleaved into each packing-only PV gap, last PV gap empty (no VALU tail after the last MFMA)
# speedup vs baseline: 1.0181x; 1.0054x over previous
; __device__ __forceinline__ void finishSM2(f32x16& p0, f32x16& p1, float alpha, float& l_reg, bf16x8& pa0, bf16x8& pa1, bf16x8& pa2, bf16x8& pa3) {
; #pragma unroll
;   for (int r = 0; r < 16; ++r) p1[r] = __builtin_amdgcn_exp2f(p1[r]);
;   float ps = 0;
; #pragma unroll
;   for (int r = 0; r < 16; ++r) ps += p0[r];
; #pragma unroll
;   for (int r = 0; r < 16; ++r) ps += p1[r];
;   { auto rr = __builtin_amdgcn_permlane32_swap(__float_as_uint(ps), __float_as_uint(ps), false, false);
;     ps = __uint_as_float(rr[0]) + __uint_as_float(rr[1]); }
;   l_reg = l_reg * alpha + ps;
;     ...
;   PK8(p0, 0, pa0); PK8(p0, 8, pa1); PK8(p1, 0, pa2); PK8(p1, 8, pa3);
;     ...
; }
; __device__ __forceinline__ void kload12(bf16x8* kf, const LAS char* Ks, int r32, int hi) {
;   const LAS char* kb = Ks + hi * 1024 + r32 * 16;
; #pragma unroll
;   for (int d0 = 0; d0 < 6; ++d0) { kf[2 * d0] = *(const LAS bf16x8*)(kb + d0 * 2048); kf[2 * d0 + 1] = *(const LAS bf16x8*)(kb + d0 * 2048 + 512); }
; }
; __device__ __forceinline__ void qkt3(f32x16& p0, f32x16& p1, const bf16x8* kf, const bf16x8* qr) {
;   p0 = f32x16{}; p1 = f32x16{};
; #pragma unroll
;   for (int d0 = 0; d0 < 6; ++d0) {
;     p0 = __builtin_amdgcn_mfma_f32_32x32x16_bf16(kf[2 * d0], qr[d0], p0, 0, 0, 0);
;     p1 = __builtin_amdgcn_mfma_f32_32x32x16_bf16(kf[2 * d0 + 1], qr[d0], p1, 0, 0, 0); }
; }
; __device__ __forceinline__ void vload16(s16x4* vf, int vb) {
;   vf[0] = tr_read<0>(vb); vf[1] = tr_read<512>(vb); vf[2] = tr_read<1024>(vb); vf[3] = tr_read<1536>(vb);
;   vf[4] = tr_read<2048>(vb); vf[5] = tr_read<2560>(vb); vf[6] = tr_read<3072>(vb); vf[7] = tr_read<3584>(vb);
;   vf[8] = tr_read<4096>(vb); vf[9] = tr_read<4608>(vb); vf[10] = tr_read<5120>(vb); vf[11] = tr_read<5632>(vb);
;   vf[12] = tr_read<6144>(vb); vf[13] = tr_read<6656>(vb); vf[14] = tr_read<7168>(vb); vf[15] = tr_read<7680>(vb);
; }
; __device__ __forceinline__ void pv3(f32x16* o, const s16x4* vf, bf16x8 pa0, bf16x8 pa1, bf16x8 pa2, bf16x8 pa3) {
;     ...
;   o[0] = __builtin_amdgcn_mfma_f32_32x32x16_bf16(pa0, PKV(0), o[0], 0, 0, 0);
;   o[1] = __builtin_amdgcn_mfma_f32_32x32x16_bf16(pa0, PKV(8), o[1], 0, 0, 0);
;   o[0] = __builtin_amdgcn_mfma_f32_32x32x16_bf16(pa1, PKV(2), o[0], 0, 0, 0);
;   o[1] = __builtin_amdgcn_mfma_f32_32x32x16_bf16(pa1, PKV(10), o[1], 0, 0, 0);
;   o[0] = __builtin_amdgcn_mfma_f32_32x32x16_bf16(pa2, PKV(4), o[0], 0, 0, 0);
.Lwd_a:
	s_barrier
	s_waitcnt lgkmcnt(0)
	s_setprio 1
	v_mfma_f32_32x32x16_bf16 v[80:95], v[48:51], v[116:119], v[238:253]
	v_exp_f32_e32 v64, v64
	v_add_f32_e32 v213, v32, v213
	ds_read_b64_tr_b16 v[148:149], v217 offset:0
	v_exp_f32_e32 v65, v65
	v_add_f32_e32 v213, v33, v213
	ds_read_b64_tr_b16 v[150:151], v217 offset:512
	v_mfma_f32_32x32x16_bf16 v[48:63], v[52:55], v[116:119], v[238:253]
	v_exp_f32_e32 v66, v66
	v_add_f32_e32 v213, v34, v213
	ds_read_b64_tr_b16 v[140:141], v217 offset:1024
	v_exp_f32_e32 v67, v67
	v_add_f32_e32 v213, v35, v213
	ds_read_b64_tr_b16 v[142:143], v217 offset:1536
	v_mfma_f32_32x32x16_bf16 v[80:95], v[188:191], v[112:115], v[80:95]
	v_exp_f32_e32 v68, v68
	v_add_f32_e32 v213, v36, v213
	ds_read_b64_tr_b16 v[132:133], v217 offset:2048
	v_exp_f32_e32 v69, v69
	v_add_f32_e32 v213, v37, v213
	ds_read_b64_tr_b16 v[134:135], v217 offset:2560
	v_mfma_f32_32x32x16_bf16 v[48:63], v[184:187], v[112:115], v[48:63]
	v_exp_f32_e32 v70, v70
	v_add_f32_e32 v213, v38, v213
	ds_read_b64_tr_b16 v[124:125], v217 offset:3072
	v_exp_f32_e32 v71, v71
	v_add_f32_e32 v213, v39, v213
	ds_read_b64_tr_b16 v[126:127], v217 offset:3584
	v_mfma_f32_32x32x16_bf16 v[80:95], v[180:183], v[108:111], v[80:95]
	v_exp_f32_e32 v72, v72
	v_add_f32_e32 v213, v40, v213
	ds_read_b64_tr_b16 v[144:145], v217 offset:4096
	v_exp_f32_e32 v73, v73
	v_add_f32_e32 v213, v41, v213
	ds_read_b64_tr_b16 v[146:147], v217 offset:4608
	v_mfma_f32_32x32x16_bf16 v[48:63], v[176:179], v[108:111], v[48:63]
	v_exp_f32_e32 v74, v74
	v_add_f32_e32 v213, v42, v213
	ds_read_b64_tr_b16 v[136:137], v217 offset:5120
	v_exp_f32_e32 v75, v75
	v_add_f32_e32 v213, v43, v213
	ds_read_b64_tr_b16 v[138:139], v217 offset:5632
	v_mfma_f32_32x32x16_bf16 v[80:95], v[172:175], v[104:107], v[80:95]
	v_exp_f32_e32 v76, v76
	v_add_f32_e32 v213, v44, v213
	ds_read_b64_tr_b16 v[128:129], v217 offset:6144
	v_exp_f32_e32 v77, v77
	v_add_f32_e32 v213, v45, v213
	ds_read_b64_tr_b16 v[130:131], v217 offset:6656
	v_mfma_f32_32x32x16_bf16 v[48:63], v[168:171], v[104:107], v[48:63]
	v_exp_f32_e32 v78, v78
	v_add_f32_e32 v213, v46, v213
	ds_read_b64_tr_b16 v[120:121], v217 offset:7168
	v_exp_f32_e32 v79, v79
	v_add_f32_e32 v213, v47, v213
	ds_read_b64_tr_b16 v[122:123], v217 offset:7680
	v_mfma_f32_32x32x16_bf16 v[80:95], v[164:167], v[100:103], v[80:95]
	v_add_f32_e32 v237, v64, v65
	v_add_f32_e32 v237, v66, v237
	v_add_f32_e32 v237, v67, v237
	v_add_f32_e32 v237, v68, v237
	v_add_f32_e32 v237, v69, v237
	v_add_f32_e32 v237, v70, v237
	v_mfma_f32_32x32x16_bf16 v[48:63], v[160:163], v[100:103], v[48:63]
	v_add_f32_e32 v237, v71, v237
	v_add_f32_e32 v237, v72, v237
	v_add_f32_e32 v237, v73, v237
	v_add_f32_e32 v237, v74, v237
	v_add_f32_e32 v237, v75, v237
	v_mfma_f32_32x32x16_bf16 v[80:95], v[156:159], v[96:99], v[80:95]
	v_add_f32_e32 v237, v76, v237
	v_add_f32_e32 v237, v77, v237
	v_add_f32_e32 v237, v78, v237
	v_add_f32_e32 v237, v79, v237
	v_add_f32_e32 v213, v237, v213
	v_cvt_pk_bf16_f32 v32, v32, v33
	v_mfma_f32_32x32x16_bf16 v[48:63], v[152:155], v[96:99], v[48:63]
	v_cvt_pk_bf16_f32 v33, v34, v35
	v_cvt_pk_bf16_f32 v34, v36, v37
	v_cvt_pk_bf16_f32 v35, v38, v39
	v_cvt_pk_bf16_f32 v36, v40, v41
	v_cvt_pk_bf16_f32 v37, v42, v43
	v_cvt_pk_bf16_f32 v38, v44, v45
	s_waitcnt lgkmcnt(0)
	v_mfma_f32_32x32x16_bf16 v[0:15], v[32:35], v[148:151], v[0:15]
	v_cvt_pk_bf16_f32 v39, v46, v47
	v_exp_f32_e32 v40, v88
	v_cvt_pk_bf16_f32 v64, v64, v65
	v_cvt_pk_bf16_f32 v65, v66, v67
	v_cvt_pk_bf16_f32 v66, v68, v69
	v_mfma_f32_32x32x16_bf16 v[16:31], v[32:35], v[144:147], v[16:31]
	v_cvt_pk_bf16_f32 v67, v70, v71
	v_exp_f32_e32 v41, v89
	v_cvt_pk_bf16_f32 v68, v72, v73
	v_cvt_pk_bf16_f32 v69, v74, v75
	v_cvt_pk_bf16_f32 v70, v76, v77
	v_cvt_pk_bf16_f32 v71, v78, v79
	v_mfma_f32_32x32x16_bf16 v[0:15], v[36:39], v[140:143], v[0:15]
	v_exp_f32_e32 v42, v90
	v_exp_f32_e32 v43, v91
	v_exp_f32_e32 v44, v92
	v_mfma_f32_32x32x16_bf16 v[16:31], v[36:39], v[136:139], v[16:31]
	v_exp_f32_e32 v45, v93
	v_exp_f32_e32 v46, v94
	v_exp_f32_e32 v47, v95
	v_mfma_f32_32x32x16_bf16 v[0:15], v[64:67], v[132:135], v[0:15]
	v_exp_f32_e32 v32, v80
	v_exp_f32_e32 v33, v81
	v_exp_f32_e32 v34, v82
	v_mfma_f32_32x32x16_bf16 v[16:31], v[64:67], v[128:131], v[16:31]
	v_exp_f32_e32 v35, v83
	v_exp_f32_e32 v36, v84
	v_exp_f32_e32 v37, v85
	v_mfma_f32_32x32x16_bf16 v[0:15], v[68:71], v[124:127], v[0:15]
	v_exp_f32_e32 v38, v86
	v_exp_f32_e32 v39, v87
	v_mfma_f32_32x32x16_bf16 v[16:31], v[68:71], v[120:123], v[16:31]
	s_setprio 0
	s_barrier
	v_max3_f32 v215, v80, v81, v82
	v_max3_f32 v215, v215, v83, v84
	v_max3_f32 v215, v215, v85, v86
	v_max3_f32 v215, v215, v87, v88
	v_max3_f32 v215, v215, v89, v90
	v_max3_f32 v215, v215, v91, v92
	v_max3_f32 v215, v215, v93, v94
	v_max3_f32 v215, v215, v95, v48
	v_max3_f32 v215, v215, v49, v50
	v_max3_f32 v215, v215, v51, v52
	v_max3_f32 v215, v215, v53, v54
	v_max3_f32 v215, v215, v55, v56
	v_max3_f32 v215, v215, v57, v58
	v_max3_f32 v215, v215, v59, v60
	v_max3_f32 v215, v215, v61, v62
	v_max_f32_e32 v215, v215, v63
	v_cmp_nge_f32_e32 vcc, s23, v215
	s_nop 3
	s_cmp_lg_u64 vcc, 0
	s_cbranch_scc1 .Lrare_a

; __device__ __forceinline__ void finishSM2(f32x16& p0, f32x16& p1, float alpha, float& l_reg, bf16x8& pa0, bf16x8& pa1, bf16x8& pa2, bf16x8& pa3) {
; #pragma unroll
;   for (int r = 0; r < 16; ++r) p1[r] = __builtin_amdgcn_exp2f(p1[r]);
;   float ps = 0;
; #pragma unroll
;   for (int r = 0; r < 16; ++r) ps += p0[r];
; #pragma unroll
;   for (int r = 0; r < 16; ++r) ps += p1[r];
;   { auto rr = __builtin_amdgcn_permlane32_swap(__float_as_uint(ps), __float_as_uint(ps), false, false);
;     ps = __uint_as_float(rr[0]) + __uint_as_float(rr[1]); }
;   l_reg = l_reg * alpha + ps;
;     ...
;   PK8(p0, 0, pa0); PK8(p0, 8, pa1); PK8(p1, 0, pa2); PK8(p1, 8, pa3);
;     ...
; }
; __device__ __forceinline__ void kload12(bf16x8* kf, const LAS char* Ks, int r32, int hi) {
;   const LAS char* kb = Ks + hi * 1024 + r32 * 16;
; #pragma unroll
;   for (int d0 = 0; d0 < 6; ++d0) { kf[2 * d0] = *(const LAS bf16x8*)(kb + d0 * 2048); kf[2 * d0 + 1] = *(const LAS bf16x8*)(kb + d0 * 2048 + 512); }
; }
; __device__ __forceinline__ void qkt3(f32x16& p0, f32x16& p1, const bf16x8* kf, const bf16x8* qr) {
;   p0 = f32x16{}; p1 = f32x16{};
; #pragma unroll
;   for (int d0 = 0; d0 < 6; ++d0) {
;     p0 = __builtin_amdgcn_mfma_f32_32x32x16_bf16(kf[2 * d0], qr[d0], p0, 0, 0, 0);
;     p1 = __builtin_amdgcn_mfma_f32_32x32x16_bf16(kf[2 * d0 + 1], qr[d0], p1, 0, 0, 0); }
; }
; __device__ __forceinline__ void vload16(s16x4* vf, int vb) {
;   vf[0] = tr_read<0>(vb); vf[1] = tr_read<512>(vb); vf[2] = tr_read<1024>(vb); vf[3] = tr_read<1536>(vb);
;   vf[4] = tr_read<2048>(vb); vf[5] = tr_read<2560>(vb); vf[6] = tr_read<3072>(vb); vf[7] = tr_read<3584>(vb);
;   vf[8] = tr_read<4096>(vb); vf[9] = tr_read<4608>(vb); vf[10] = tr_read<5120>(vb); vf[11] = tr_read<5632>(vb);
;   vf[12] = tr_read<6144>(vb); vf[13] = tr_read<6656>(vb); vf[14] = tr_read<7168>(vb); vf[15] = tr_read<7680>(vb);
; }
; __device__ __forceinline__ void pv3(f32x16* o, const s16x4* vf, bf16x8 pa0, bf16x8 pa1, bf16x8 pa2, bf16x8 pa3) {
;     ...
;   o[0] = __builtin_amdgcn_mfma_f32_32x32x16_bf16(pa0, PKV(0), o[0], 0, 0, 0);
;   o[1] = __builtin_amdgcn_mfma_f32_32x32x16_bf16(pa0, PKV(8), o[1], 0, 0, 0);
;   o[0] = __builtin_amdgcn_mfma_f32_32x32x16_bf16(pa1, PKV(2), o[0], 0, 0, 0);
;   o[1] = __builtin_amdgcn_mfma_f32_32x32x16_bf16(pa1, PKV(10), o[1], 0, 0, 0);
;   o[0] = __builtin_amdgcn_mfma_f32_32x32x16_bf16(pa2, PKV(4), o[0], 0, 0, 0);
.Lwd_b:
	s_barrier
	s_waitcnt lgkmcnt(0)
	s_setprio 1
	v_mfma_f32_32x32x16_bf16 v[80:95], v[64:67], v[116:119], v[238:253]
	v_exp_f32_e32 v48, v48
	v_add_f32_e32 v213, v32, v213
	ds_read_b64_tr_b16 v[148:149], v217 offset:0
	v_exp_f32_e32 v49, v49
	v_add_f32_e32 v213, v33, v213
	ds_read_b64_tr_b16 v[150:151], v217 offset:512
	v_mfma_f32_32x32x16_bf16 v[64:79], v[68:71], v[116:119], v[238:253]
	v_exp_f32_e32 v50, v50
	v_add_f32_e32 v213, v34, v213
	ds_read_b64_tr_b16 v[140:141], v217 offset:1024
	v_exp_f32_e32 v51, v51
	v_add_f32_e32 v213, v35, v213
	ds_read_b64_tr_b16 v[142:143], v217 offset:1536
	v_mfma_f32_32x32x16_bf16 v[80:95], v[188:191], v[112:115], v[80:95]
	v_exp_f32_e32 v52, v52
	v_add_f32_e32 v213, v36, v213
	ds_read_b64_tr_b16 v[132:133], v217 offset:2048
	v_exp_f32_e32 v53, v53
	v_add_f32_e32 v213, v37, v213
	ds_read_b64_tr_b16 v[134:135], v217 offset:2560
	v_mfma_f32_32x32x16_bf16 v[64:79], v[184:187], v[112:115], v[64:79]
	v_exp_f32_e32 v54, v54
	v_add_f32_e32 v213, v38, v213
	ds_read_b64_tr_b16 v[124:125], v217 offset:3072
	v_exp_f32_e32 v55, v55
	v_add_f32_e32 v213, v39, v213
	ds_read_b64_tr_b16 v[126:127], v217 offset:3584
	v_mfma_f32_32x32x16_bf16 v[80:95], v[180:183], v[108:111], v[80:95]
	v_exp_f32_e32 v56, v56
	v_add_f32_e32 v213, v40, v213
	ds_read_b64_tr_b16 v[144:145], v217 offset:4096
	v_exp_f32_e32 v57, v57
	v_add_f32_e32 v213, v41, v213
	ds_read_b64_tr_b16 v[146:147], v217 offset:4608
	v_mfma_f32_32x32x16_bf16 v[64:79], v[176:179], v[108:111], v[64:79]
	v_exp_f32_e32 v58, v58
	v_add_f32_e32 v213, v42, v213
	ds_read_b64_tr_b16 v[136:137], v217 offset:5120
	v_exp_f32_e32 v59, v59
	v_add_f32_e32 v213, v43, v213
	ds_read_b64_tr_b16 v[138:139], v217 offset:5632
	v_mfma_f32_32x32x16_bf16 v[80:95], v[172:175], v[104:107], v[80:95]
	v_exp_f32_e32 v60, v60
	v_add_f32_e32 v213, v44, v213
	ds_read_b64_tr_b16 v[128:129], v217 offset:6144
	v_exp_f32_e32 v61, v61
	v_add_f32_e32 v213, v45, v213
	ds_read_b64_tr_b16 v[130:131], v217 offset:6656
	v_mfma_f32_32x32x16_bf16 v[64:79], v[168:171], v[104:107], v[64:79]
	v_exp_f32_e32 v62, v62
	v_add_f32_e32 v213, v46, v213
	ds_read_b64_tr_b16 v[120:121], v217 offset:7168
	v_exp_f32_e32 v63, v63
	v_add_f32_e32 v213, v47, v213
	ds_read_b64_tr_b16 v[122:123], v217 offset:7680
	v_mfma_f32_32x32x16_bf16 v[80:95], v[164:167], v[100:103], v[80:95]
	v_add_f32_e32 v237, v48, v49
	v_add_f32_e32 v237, v50, v237
	v_add_f32_e32 v237, v51, v237
	v_add_f32_e32 v237, v52, v237
	v_add_f32_e32 v237, v53, v237
	v_add_f32_e32 v237, v54, v237
	v_mfma_f32_32x32x16_bf16 v[64:79], v[160:163], v[100:103], v[64:79]
	v_add_f32_e32 v237, v55, v237
	v_add_f32_e32 v237, v56, v237
	v_add_f32_e32 v237, v57, v237
	v_add_f32_e32 v237, v58, v237
	v_add_f32_e32 v237, v59, v237
	v_mfma_f32_32x32x16_bf16 v[80:95], v[156:159], v[96:99], v[80:95]
	v_add_f32_e32 v237, v60, v237
	v_add_f32_e32 v237, v61, v237
	v_add_f32_e32 v237, v62, v237
	v_add_f32_e32 v237, v63, v237
	v_add_f32_e32 v213, v237, v213
	v_cvt_pk_bf16_f32 v32, v32, v33
	v_mfma_f32_32x32x16_bf16 v[64:79], v[152:155], v[96:99], v[64:79]
	v_cvt_pk_bf16_f32 v33, v34, v35
	v_cvt_pk_bf16_f32 v34, v36, v37
	v_cvt_pk_bf16_f32 v35, v38, v39
	v_cvt_pk_bf16_f32 v36, v40, v41
	v_cvt_pk_bf16_f32 v37, v42, v43
	v_cvt_pk_bf16_f32 v38, v44, v45
	s_waitcnt lgkmcnt(0)
	v_mfma_f32_32x32x16_bf16 v[0:15], v[32:35], v[148:151], v[0:15]
	v_cvt_pk_bf16_f32 v39, v46, v47
	v_exp_f32_e32 v40, v88
	v_cvt_pk_bf16_f32 v48, v48, v49
	v_cvt_pk_bf16_f32 v49, v50, v51
	v_cvt_pk_bf16_f32 v50, v52, v53
	v_mfma_f32_32x32x16_bf16 v[16:31], v[32:35], v[144:147], v[16:31]
	v_cvt_pk_bf16_f32 v51, v54, v55
	v_exp_f32_e32 v41, v89
	v_cvt_pk_bf16_f32 v52, v56, v57
	v_cvt_pk_bf16_f32 v53, v58, v59
	v_cvt_pk_bf16_f32 v54, v60, v61
	v_cvt_pk_bf16_f32 v55, v62, v63
	v_mfma_f32_32x32x16_bf16 v[0:15], v[36:39], v[140:143], v[0:15]
	v_exp_f32_e32 v42, v90
	v_exp_f32_e32 v43, v91
	v_exp_f32_e32 v44, v92
	v_mfma_f32_32x32x16_bf16 v[16:31], v[36:39], v[136:139], v[16:31]
	v_exp_f32_e32 v45, v93
	v_exp_f32_e32 v46, v94
	v_exp_f32_e32 v47, v95
	v_mfma_f32_32x32x16_bf16 v[0:15], v[48:51], v[132:135], v[0:15]
	v_exp_f32_e32 v32, v80
	v_exp_f32_e32 v33, v81
	v_exp_f32_e32 v34, v82
	v_mfma_f32_32x32x16_bf16 v[16:31], v[48:51], v[128:131], v[16:31]
	v_exp_f32_e32 v35, v83
	v_exp_f32_e32 v36, v84
	v_exp_f32_e32 v37, v85
	v_mfma_f32_32x32x16_bf16 v[0:15], v[52:55], v[124:127], v[0:15]
	v_exp_f32_e32 v38, v86
	v_exp_f32_e32 v39, v87
	v_mfma_f32_32x32x16_bf16 v[16:31], v[52:55], v[120:123], v[16:31]
	s_setprio 0
	s_add_i32 s6, s6, 2
	s_barrier
	s_addk_i32 s63, 0x4000
	v_lshl_add_u64 v[220:221], v[220:221], 0, s[12:13]
	v_lshl_add_u64 v[222:223], v[222:223], 0, s[10:11]
	v_lshl_add_u64 v[224:225], v[224:225], 0, s[10:11]
	s_and_b64 vcc, exec, s[58:59]
	s_cbranch_vccnz .LBB0_597
	s_mov_b32 s68, s70
	s_mov_b32 s70, s71
	s_branch .LBB0_570

; __device__ __forceinline__ void finishSM2(f32x16& p0, f32x16& p1, float alpha, float& l_reg, bf16x8& pa0, bf16x8& pa1, bf16x8& pa2, bf16x8& pa3) {
; #pragma unroll
;   for (int r = 0; r < 16; ++r) p1[r] = __builtin_amdgcn_exp2f(p1[r]);
;   float ps = 0;
; #pragma unroll
;   for (int r = 0; r < 16; ++r) ps += p0[r];
; #pragma unroll
;   for (int r = 0; r < 16; ++r) ps += p1[r];
;   { auto rr = __builtin_amdgcn_permlane32_swap(__float_as_uint(ps), __float_as_uint(ps), false, false);
;     ps = __uint_as_float(rr[0]) + __uint_as_float(rr[1]); }
;   l_reg = l_reg * alpha + ps;
;     ...
;   PK8(p0, 0, pa0); PK8(p0, 8, pa1); PK8(p1, 0, pa2); PK8(p1, 8, pa3);
;     ...
; }
; __device__ __forceinline__ void kload12(bf16x8* kf, const LAS char* Ks, int r32, int hi) {
;   const LAS char* kb = Ks + hi * 1024 + r32 * 16;
; #pragma unroll
;   for (int d0 = 0; d0 < 6; ++d0) { kf[2 * d0] = *(const LAS bf16x8*)(kb + d0 * 2048); kf[2 * d0 + 1] = *(const LAS bf16x8*)(kb + d0 * 2048 + 512); }
; }
; __device__ __forceinline__ void qkt3(f32x16& p0, f32x16& p1, const bf16x8* kf, const bf16x8* qr) {
;   p0 = f32x16{}; p1 = f32x16{};
; #pragma unroll
;   for (int d0 = 0; d0 < 6; ++d0) {
;     p0 = __builtin_amdgcn_mfma_f32_32x32x16_bf16(kf[2 * d0], qr[d0], p0, 0, 0, 0);
;     p1 = __builtin_amdgcn_mfma_f32_32x32x16_bf16(kf[2 * d0 + 1], qr[d0], p1, 0, 0, 0); }
; }
; __device__ __forceinline__ void vload16(s16x4* vf, int vb) {
;   vf[0] = tr_read<0>(vb); vf[1] = tr_read<512>(vb); vf[2] = tr_read<1024>(vb); vf[3] = tr_read<1536>(vb);
;   vf[4] = tr_read<2048>(vb); vf[5] = tr_read<2560>(vb); vf[6] = tr_read<3072>(vb); vf[7] = tr_read<3584>(vb);
;   vf[8] = tr_read<4096>(vb); vf[9] = tr_read<4608>(vb); vf[10] = tr_read<5120>(vb); vf[11] = tr_read<5632>(vb);
;   vf[12] = tr_read<6144>(vb); vf[13] = tr_read<6656>(vb); vf[14] = tr_read<7168>(vb); vf[15] = tr_read<7680>(vb);
; }
; __device__ __forceinline__ void pv3(f32x16* o, const s16x4* vf, bf16x8 pa0, bf16x8 pa1, bf16x8 pa2, bf16x8 pa3) {
;     ...
;   o[0] = __builtin_amdgcn_mfma_f32_32x32x16_bf16(pa0, PKV(0), o[0], 0, 0, 0);
;   o[1] = __builtin_amdgcn_mfma_f32_32x32x16_bf16(pa0, PKV(8), o[1], 0, 0, 0);
;   o[0] = __builtin_amdgcn_mfma_f32_32x32x16_bf16(pa1, PKV(2), o[0], 0, 0, 0);
;   o[1] = __builtin_amdgcn_mfma_f32_32x32x16_bf16(pa1, PKV(10), o[1], 0, 0, 0);
;   o[0] = __builtin_amdgcn_mfma_f32_32x32x16_bf16(pa2, PKV(4), o[0], 0, 0, 0);
.Ljoin_u:
	ds_read_b128 v[48:51], v231 offset:36864
	ds_read_b128 v[52:55], v231 offset:37376
	ds_read_b128 v[188:191], v231 offset:38912
	ds_read_b128 v[184:187], v231 offset:39424
	ds_read_b128 v[180:183], v231 offset:40960
	ds_read_b128 v[176:179], v231 offset:41472
	ds_read_b128 v[172:175], v231 offset:43008
	ds_read_b128 v[168:171], v231 offset:43520
	ds_read_b128 v[164:167], v231 offset:45056
	ds_read_b128 v[160:163], v231 offset:45568
	ds_read_b128 v[156:159], v231 offset:47104
	ds_read_b128 v[152:155], v231 offset:47616
	s_waitcnt vmcnt(0) lgkmcnt(0)
	s_barrier
	s_waitcnt lgkmcnt(0)
	s_setprio 1
	v_mfma_f32_32x32x16_bf16 v[80:95], v[48:51], v[116:119], v[238:253]
	v_exp_f32_e32 v64, v64
	v_add_f32_e32 v213, v32, v213
	ds_read_b64_tr_b16 v[148:149], v233 offset:0
	v_exp_f32_e32 v65, v65
	v_add_f32_e32 v213, v33, v213
	ds_read_b64_tr_b16 v[150:151], v233 offset:512
	v_mfma_f32_32x32x16_bf16 v[48:63], v[52:55], v[116:119], v[238:253]
	v_exp_f32_e32 v66, v66
	v_add_f32_e32 v213, v34, v213
	ds_read_b64_tr_b16 v[140:141], v233 offset:1024
	v_exp_f32_e32 v67, v67
	v_add_f32_e32 v213, v35, v213
	ds_read_b64_tr_b16 v[142:143], v233 offset:1536
	v_mfma_f32_32x32x16_bf16 v[80:95], v[188:191], v[112:115], v[80:95]
	v_exp_f32_e32 v68, v68
	v_add_f32_e32 v213, v36, v213
	ds_read_b64_tr_b16 v[132:133], v233 offset:2048
	v_exp_f32_e32 v69, v69
	v_add_f32_e32 v213, v37, v213
	ds_read_b64_tr_b16 v[134:135], v233 offset:2560
	v_mfma_f32_32x32x16_bf16 v[48:63], v[184:187], v[112:115], v[48:63]
	v_exp_f32_e32 v70, v70
	v_add_f32_e32 v213, v38, v213
	ds_read_b64_tr_b16 v[124:125], v233 offset:3072
	v_exp_f32_e32 v71, v71
	v_add_f32_e32 v213, v39, v213
	ds_read_b64_tr_b16 v[126:127], v233 offset:3584
	v_mfma_f32_32x32x16_bf16 v[80:95], v[180:183], v[108:111], v[80:95]
	v_exp_f32_e32 v72, v72
	v_add_f32_e32 v213, v40, v213
	ds_read_b64_tr_b16 v[144:145], v233 offset:4096
	v_exp_f32_e32 v73, v73
	v_add_f32_e32 v213, v41, v213
	ds_read_b64_tr_b16 v[146:147], v233 offset:4608
	v_mfma_f32_32x32x16_bf16 v[48:63], v[176:179], v[108:111], v[48:63]
	v_exp_f32_e32 v74, v74
	v_add_f32_e32 v213, v42, v213
	ds_read_b64_tr_b16 v[136:137], v233 offset:5120
	v_exp_f32_e32 v75, v75
	v_add_f32_e32 v213, v43, v213
	ds_read_b64_tr_b16 v[138:139], v233 offset:5632
	v_mfma_f32_32x32x16_bf16 v[80:95], v[172:175], v[104:107], v[80:95]
	v_exp_f32_e32 v76, v76
	v_add_f32_e32 v213, v44, v213
	ds_read_b64_tr_b16 v[128:129], v233 offset:6144
	v_exp_f32_e32 v77, v77
	v_add_f32_e32 v213, v45, v213
	ds_read_b64_tr_b16 v[130:131], v233 offset:6656
	v_mfma_f32_32x32x16_bf16 v[48:63], v[168:171], v[104:107], v[48:63]
	v_exp_f32_e32 v78, v78
	v_add_f32_e32 v213, v46, v213
	ds_read_b64_tr_b16 v[120:121], v233 offset:7168
	v_exp_f32_e32 v79, v79
	v_add_f32_e32 v213, v47, v213
	ds_read_b64_tr_b16 v[122:123], v233 offset:7680
	v_mfma_f32_32x32x16_bf16 v[80:95], v[164:167], v[100:103], v[80:95]
	v_add_f32_e32 v237, v64, v65
	v_add_f32_e32 v237, v66, v237
	v_add_f32_e32 v237, v67, v237
	v_add_f32_e32 v237, v68, v237
	v_add_f32_e32 v237, v69, v237
	v_add_f32_e32 v237, v70, v237
	v_mfma_f32_32x32x16_bf16 v[48:63], v[160:163], v[100:103], v[48:63]
	v_add_f32_e32 v237, v71, v237
	v_add_f32_e32 v237, v72, v237
	v_add_f32_e32 v237, v73, v237
	v_add_f32_e32 v237, v74, v237
	v_add_f32_e32 v237, v75, v237
	v_mfma_f32_32x32x16_bf16 v[80:95], v[156:159], v[96:99], v[80:95]
	v_add_f32_e32 v237, v76, v237
	v_add_f32_e32 v237, v77, v237
	v_add_f32_e32 v237, v78, v237
	v_add_f32_e32 v237, v79, v237
	v_add_f32_e32 v213, v237, v213
	v_cvt_pk_bf16_f32 v32, v32, v33
	v_mfma_f32_32x32x16_bf16 v[48:63], v[152:155], v[96:99], v[48:63]
	v_cvt_pk_bf16_f32 v33, v34, v35
	v_cvt_pk_bf16_f32 v34, v36, v37
	v_cvt_pk_bf16_f32 v35, v38, v39
	v_cvt_pk_bf16_f32 v36, v40, v41
	v_cvt_pk_bf16_f32 v37, v42, v43
	v_cvt_pk_bf16_f32 v38, v44, v45
	s_waitcnt lgkmcnt(0)
	v_mfma_f32_32x32x16_bf16 v[0:15], v[32:35], v[148:151], v[0:15]
	v_cvt_pk_bf16_f32 v39, v46, v47
	v_exp_f32_e32 v40, v88
	v_cvt_pk_bf16_f32 v64, v64, v65
	v_cvt_pk_bf16_f32 v65, v66, v67
	v_cvt_pk_bf16_f32 v66, v68, v69
	v_mfma_f32_32x32x16_bf16 v[16:31], v[32:35], v[144:147], v[16:31]
	v_cvt_pk_bf16_f32 v67, v70, v71
	v_exp_f32_e32 v41, v89
	v_cvt_pk_bf16_f32 v68, v72, v73
	v_cvt_pk_bf16_f32 v69, v74, v75
	v_cvt_pk_bf16_f32 v70, v76, v77
	v_cvt_pk_bf16_f32 v71, v78, v79
	v_mfma_f32_32x32x16_bf16 v[0:15], v[36:39], v[140:143], v[0:15]
	v_exp_f32_e32 v42, v90
	v_exp_f32_e32 v43, v91
	v_exp_f32_e32 v44, v92
	v_mfma_f32_32x32x16_bf16 v[16:31], v[36:39], v[136:139], v[16:31]
	v_exp_f32_e32 v45, v93
	v_exp_f32_e32 v46, v94
	v_exp_f32_e32 v47, v95
	v_mfma_f32_32x32x16_bf16 v[0:15], v[64:67], v[132:135], v[0:15]
	v_exp_f32_e32 v32, v80
	v_exp_f32_e32 v33, v81
	v_exp_f32_e32 v34, v82
	v_mfma_f32_32x32x16_bf16 v[16:31], v[64:67], v[128:131], v[16:31]
	v_exp_f32_e32 v35, v83
	v_exp_f32_e32 v36, v84
	v_exp_f32_e32 v37, v85
	v_mfma_f32_32x32x16_bf16 v[0:15], v[68:71], v[124:127], v[0:15]
	v_exp_f32_e32 v38, v86
	v_exp_f32_e32 v39, v87
	v_mfma_f32_32x32x16_bf16 v[16:31], v[68:71], v[120:123], v[16:31]
	s_setprio 0
	s_barrier
	s_and_b64 vcc, exec, s[4:5]
	s_cbranch_vccnz .LBB0_603
	s_barrier
